# barriers 3->4 and 4->5 without the XCD L2 write-back (panels are XCD-local); sample-row unit stores write-through
# baseline (speedup 1.0000x reference)
.LBB0_1020:
	s_lshr_b32 s7, s6, 2
	s_and_b32 s1, s6, 7
	s_and_b32 s0, s3, 0xc0
	s_and_b32 s7, s7, 0x3fffff8
	s_bitset1_b32 s0, 14
	s_or_b32 s1, s7, s1
	s_lshl_b32 s1, s1, 6
	v_add_lshl_u32 v2, s0, v1, 11
	v_lshl_add_u64 v[116:117], v[4:5], 0, v[2:3]
	v_add_lshl_u32 v2, s1, v1, 11
	v_lshl_add_u64 v[118:119], v[6:7], 0, v[2:3]
	s_waitcnt lgkmcnt(0)
	global_load_dwordx4 v[20:23], v[116:117], off
	global_load_dwordx4 v[24:27], v[116:117], off offset:128
	global_load_dwordx4 v[28:31], v[118:119], off
	global_load_dwordx4 v[32:35], v[118:119], off offset:128
	global_load_dwordx4 v[36:39], v[116:117], off offset:256
	global_load_dwordx4 v[40:43], v[116:117], off offset:384
	global_load_dwordx4 v[44:47], v[118:119], off offset:256
	global_load_dwordx4 v[48:51], v[118:119], off offset:384
	global_load_dwordx4 v[52:55], v[116:117], off offset:512
	global_load_dwordx4 v[56:59], v[116:117], off offset:640
	global_load_dwordx4 v[60:63], v[118:119], off offset:512
	global_load_dwordx4 v[64:67], v[118:119], off offset:640
	global_load_dwordx4 v[68:71], v[116:117], off offset:768
	global_load_dwordx4 v[72:75], v[116:117], off offset:896
	global_load_dwordx4 v[76:79], v[118:119], off offset:768
	global_load_dwordx4 v[80:83], v[118:119], off offset:896
	v_add_u32_e32 v19, s0, v9
	v_lshlrev_b32_e32 v2, 11, v19
	s_waitcnt vmcnt(0)
	ds_write_b128 v8, v[20:23]
	ds_write_b128 v8, v[24:27] offset:128
	ds_write_b128 v8, v[28:31] offset:34816
	ds_write_b128 v8, v[32:35] offset:34944
	s_waitcnt lgkmcnt(0)
	s_barrier
	ds_read_b128 v[20:23], v14 offset:34816
	ds_read_b128 v[24:27], v14 offset:43520
	ds_read_b128 v[28:31], v10
	ds_read_b128 v[32:35], v10 offset:64
	ds_read_b128 v[84:87], v14 offset:34880
	global_load_dwordx4 v[88:91], v[116:117], off offset:1024
	global_load_dwordx4 v[92:95], v[116:117], off offset:1152
	ds_read_b128 v[96:99], v14 offset:43584
	s_waitcnt lgkmcnt(3)
	v_mfma_f32_16x16x32_bf16 v[20:23], v[20:23], v[28:31], 0
	v_mfma_f32_16x16x32_bf16 v[24:27], v[24:27], v[28:31], 0
	global_load_dwordx4 v[28:31], v[118:119], off offset:1024
	global_load_dwordx4 v[100:103], v[118:119], off offset:1152
	ds_read_b128 v[104:107], v14 offset:34944
	s_waitcnt lgkmcnt(2)
	v_mfma_f32_16x16x32_bf16 v[20:23], v[84:87], v[32:35], v[20:23]
	ds_read_b128 v[84:87], v14 offset:43648
	ds_read_b128 v[108:111], v10 offset:128
	ds_read_b128 v[112:115], v10 offset:192
	s_waitcnt lgkmcnt(4)
	v_mfma_f32_16x16x32_bf16 v[24:27], v[96:99], v[32:35], v[24:27]
	ds_read_b128 v[32:35], v14 offset:35008
	ds_read_b128 v[96:99], v14 offset:43712
	ds_write_b128 v8, v[36:39] offset:17408
	ds_write_b128 v8, v[40:43] offset:17536
	ds_write_b128 v8, v[44:47] offset:52224
	ds_write_b128 v8, v[48:51] offset:52352
	s_waitcnt lgkmcnt(7)
	v_mfma_f32_16x16x32_bf16 v[20:23], v[104:107], v[108:111], v[20:23]
	s_waitcnt lgkmcnt(0)
	s_barrier
	v_mfma_f32_16x16x32_bf16 v[24:27], v[84:87], v[108:111], v[24:27]
	v_mfma_f32_16x16x32_bf16 v[20:23], v[32:35], v[112:115], v[20:23]
	ds_read_b128 v[32:35], v12 offset:52224
	ds_read_b128 v[36:39], v12 offset:60928
	ds_read_b128 v[40:43], v11
	ds_read_b128 v[44:47], v11 offset:64
	ds_read_b128 v[48:51], v12 offset:52288
	v_mfma_f32_16x16x32_bf16 v[24:27], v[96:99], v[112:115], v[24:27]
	s_waitcnt lgkmcnt(2)
	v_mfma_f32_16x16x32_bf16 v[20:23], v[32:35], v[40:43], v[20:23]
	global_load_dwordx4 v[32:35], v[116:117], off offset:1280
	global_load_dwordx4 v[84:87], v[116:117], off offset:1408
	ds_read_b128 v[96:99], v12 offset:60992
	v_mfma_f32_16x16x32_bf16 v[24:27], v[36:39], v[40:43], v[24:27]
	global_load_dwordx4 v[36:39], v[118:119], off offset:1280
	global_load_dwordx4 v[40:43], v[118:119], off offset:1408
	ds_read_b128 v[104:107], v12 offset:52352
	s_waitcnt lgkmcnt(2)
	v_mfma_f32_16x16x32_bf16 v[20:23], v[48:51], v[44:47], v[20:23]
	ds_read_b128 v[48:51], v12 offset:61056
	ds_read_b128 v[108:111], v11 offset:128
	ds_read_b128 v[112:115], v11 offset:192
	s_waitcnt lgkmcnt(4)
	v_mfma_f32_16x16x32_bf16 v[24:27], v[96:99], v[44:47], v[24:27]
	ds_read_b128 v[44:47], v12 offset:52416
	ds_read_b128 v[96:99], v12 offset:61120
	ds_write_b128 v8, v[52:55]
	ds_write_b128 v8, v[56:59] offset:128
	ds_write_b128 v8, v[60:63] offset:34816
	ds_write_b128 v8, v[64:67] offset:34944
	s_waitcnt lgkmcnt(7)
	v_mfma_f32_16x16x32_bf16 v[20:23], v[104:107], v[108:111], v[20:23]
	s_waitcnt lgkmcnt(0)
	s_barrier
	v_mfma_f32_16x16x32_bf16 v[24:27], v[48:51], v[108:111], v[24:27]
	v_mfma_f32_16x16x32_bf16 v[20:23], v[44:47], v[112:115], v[20:23]
	ds_read_b128 v[44:47], v14 offset:34816
	ds_read_b128 v[48:51], v14 offset:43520
	ds_read_b128 v[52:55], v10
	ds_read_b128 v[56:59], v10 offset:64
	ds_read_b128 v[60:63], v14 offset:34880
	v_mfma_f32_16x16x32_bf16 v[24:27], v[96:99], v[112:115], v[24:27]
	s_waitcnt lgkmcnt(2)
	v_mfma_f32_16x16x32_bf16 v[20:23], v[44:47], v[52:55], v[20:23]
	global_load_dwordx4 v[44:47], v[116:117], off offset:1536
	global_load_dwordx4 v[64:67], v[116:117], off offset:1664
	ds_read_b128 v[96:99], v14 offset:43584
	v_mfma_f32_16x16x32_bf16 v[24:27], v[48:51], v[52:55], v[24:27]
	global_load_dwordx4 v[48:51], v[118:119], off offset:1536
	global_load_dwordx4 v[52:55], v[118:119], off offset:1664
	ds_read_b128 v[104:107], v14 offset:34944
	s_waitcnt lgkmcnt(2)
	v_mfma_f32_16x16x32_bf16 v[20:23], v[60:63], v[56:59], v[20:23]
	ds_read_b128 v[60:63], v14 offset:43648
	ds_read_b128 v[108:111], v10 offset:128
	ds_read_b128 v[112:115], v10 offset:192
	s_waitcnt lgkmcnt(4)
	v_mfma_f32_16x16x32_bf16 v[24:27], v[96:99], v[56:59], v[24:27]
	ds_read_b128 v[56:59], v14 offset:35008
	ds_read_b128 v[96:99], v14 offset:43712
	ds_write_b128 v8, v[68:71] offset:17408
	ds_write_b128 v8, v[72:75] offset:17536
	ds_write_b128 v8, v[76:79] offset:52224
	ds_write_b128 v8, v[80:83] offset:52352
	s_waitcnt lgkmcnt(7)
	v_mfma_f32_16x16x32_bf16 v[20:23], v[104:107], v[108:111], v[20:23]
	s_waitcnt lgkmcnt(0)
	s_barrier
	v_mfma_f32_16x16x32_bf16 v[20:23], v[56:59], v[112:115], v[20:23]
	ds_read_b128 v[56:59], v12 offset:52224
	v_mfma_f32_16x16x32_bf16 v[24:27], v[60:63], v[108:111], v[24:27]
	ds_read_b128 v[60:63], v11
	ds_read_b128 v[68:71], v11 offset:64
	ds_read_b128 v[72:75], v12 offset:52288
	v_mfma_f32_16x16x32_bf16 v[24:27], v[96:99], v[112:115], v[24:27]
	s_waitcnt lgkmcnt(2)
	v_mfma_f32_16x16x32_bf16 v[20:23], v[56:59], v[60:63], v[20:23]
	ds_read_b128 v[56:59], v12 offset:60928
	ds_read_b128 v[76:79], v12 offset:60992
	s_waitcnt lgkmcnt(1)
	v_mfma_f32_16x16x32_bf16 v[24:27], v[56:59], v[60:63], v[24:27]
	ds_read_b128 v[56:59], v12 offset:52352
	v_mfma_f32_16x16x32_bf16 v[20:23], v[72:75], v[68:71], v[20:23]
	s_waitcnt lgkmcnt(1)
	v_mfma_f32_16x16x32_bf16 v[24:27], v[76:79], v[68:71], v[24:27]
	ds_read_b128 v[60:63], v11 offset:128
	ds_read_b128 v[68:71], v11 offset:192
	ds_read_b128 v[72:75], v12 offset:52416
	s_waitcnt lgkmcnt(2)
	v_mfma_f32_16x16x32_bf16 v[20:23], v[56:59], v[60:63], v[20:23]
	ds_read_b128 v[56:59], v12 offset:61056
	ds_read_b128 v[76:79], v12 offset:61120
	s_waitcnt lgkmcnt(1)
	v_mfma_f32_16x16x32_bf16 v[24:27], v[56:59], v[60:63], v[24:27]
	global_load_dwordx4 v[56:59], v[116:117], off offset:1792
	global_load_dwordx4 v[60:63], v[116:117], off offset:1920
	global_load_dwordx4 v[80:83], v[118:119], off offset:1792
	global_load_dwordx4 v[96:99], v[118:119], off offset:1920
	s_waitcnt vmcnt(15)
	ds_write_b128 v8, v[88:91]
	s_waitcnt vmcnt(14)
	ds_write_b128 v8, v[92:95] offset:128
	s_waitcnt vmcnt(13)
	ds_write_b128 v8, v[28:31] offset:34816
	s_waitcnt vmcnt(12)
	ds_write_b128 v8, v[100:103] offset:34944
	s_waitcnt lgkmcnt(0)
	s_barrier
	ds_read_b128 v[28:31], v14 offset:34816
	v_mfma_f32_16x16x32_bf16 v[20:23], v[72:75], v[68:71], v[20:23]
	v_mfma_f32_16x16x32_bf16 v[24:27], v[76:79], v[68:71], v[24:27]
	ds_read_b128 v[68:71], v10
	ds_read_b128 v[72:75], v10 offset:64
	ds_read_b128 v[76:79], v14 offset:34880
	s_waitcnt lgkmcnt(2)
	v_mfma_f32_16x16x32_bf16 v[20:23], v[28:31], v[68:71], v[20:23]
	ds_read_b128 v[28:31], v14 offset:43520
	ds_read_b128 v[88:91], v14 offset:43584
	s_waitcnt lgkmcnt(1)
	v_mfma_f32_16x16x32_bf16 v[24:27], v[28:31], v[68:71], v[24:27]
	ds_read_b128 v[28:31], v14 offset:34944
	v_mfma_f32_16x16x32_bf16 v[20:23], v[76:79], v[72:75], v[20:23]
	ds_read_b128 v[68:71], v14 offset:43648
	ds_read_b128 v[76:79], v10 offset:128
	ds_read_b128 v[92:95], v10 offset:192
	s_waitcnt lgkmcnt(4)
	v_mfma_f32_16x16x32_bf16 v[24:27], v[88:91], v[72:75], v[24:27]
	ds_read_b128 v[72:75], v14 offset:35008
	ds_read_b128 v[88:91], v14 offset:43712
	s_waitcnt vmcnt(11)
	ds_write_b128 v8, v[32:35] offset:17408
	s_waitcnt vmcnt(10)
	ds_write_b128 v8, v[84:87] offset:17536
	s_waitcnt vmcnt(9)
	ds_write_b128 v8, v[36:39] offset:52224
	s_waitcnt vmcnt(8)
	ds_write_b128 v8, v[40:43] offset:52352
	s_waitcnt lgkmcnt(7)
	v_mfma_f32_16x16x32_bf16 v[20:23], v[28:31], v[76:79], v[20:23]
	s_waitcnt lgkmcnt(0)
	s_barrier
	ds_read_b128 v[28:31], v12 offset:52224
	v_mfma_f32_16x16x32_bf16 v[24:27], v[68:71], v[76:79], v[24:27]
	ds_read_b128 v[32:35], v11
	ds_read_b128 v[36:39], v11 offset:64
	ds_read_b128 v[40:43], v12 offset:52288
	v_mfma_f32_16x16x32_bf16 v[20:23], v[72:75], v[92:95], v[20:23]
	v_mfma_f32_16x16x32_bf16 v[24:27], v[88:91], v[92:95], v[24:27]
	s_waitcnt lgkmcnt(2)
	v_mfma_f32_16x16x32_bf16 v[20:23], v[28:31], v[32:35], v[20:23]
	ds_read_b128 v[28:31], v12 offset:60928
	ds_read_b128 v[68:71], v12 offset:60992
	s_waitcnt lgkmcnt(1)
	v_mfma_f32_16x16x32_bf16 v[24:27], v[28:31], v[32:35], v[24:27]
	ds_read_b128 v[28:31], v12 offset:52352
	v_mfma_f32_16x16x32_bf16 v[20:23], v[40:43], v[36:39], v[20:23]
	s_waitcnt lgkmcnt(1)
	v_mfma_f32_16x16x32_bf16 v[24:27], v[68:71], v[36:39], v[24:27]
	ds_read_b128 v[32:35], v11 offset:128
	ds_read_b128 v[36:39], v11 offset:192
	ds_read_b128 v[40:43], v12 offset:52416
	s_waitcnt lgkmcnt(2)
	v_mfma_f32_16x16x32_bf16 v[20:23], v[28:31], v[32:35], v[20:23]
	ds_read_b128 v[28:31], v12 offset:61056
	ds_read_b128 v[68:71], v12 offset:61120
	s_waitcnt vmcnt(7)
	ds_write_b128 v8, v[44:47]
	s_waitcnt vmcnt(6)
	ds_write_b128 v8, v[64:67] offset:128
	s_waitcnt vmcnt(5)
	ds_write_b128 v8, v[48:51] offset:34816
	s_waitcnt vmcnt(4)
	ds_write_b128 v8, v[52:55] offset:34944
	s_waitcnt lgkmcnt(0)
	v_mfma_f32_16x16x32_bf16 v[24:27], v[28:31], v[32:35], v[24:27]
	s_barrier
	ds_read_b128 v[28:31], v14 offset:34816
	v_mfma_f32_16x16x32_bf16 v[20:23], v[40:43], v[36:39], v[20:23]
	v_mfma_f32_16x16x32_bf16 v[24:27], v[68:71], v[36:39], v[24:27]
	ds_read_b128 v[32:35], v10
	ds_read_b128 v[36:39], v10 offset:64
	ds_read_b128 v[40:43], v14 offset:34880
	s_waitcnt lgkmcnt(2)
	v_mfma_f32_16x16x32_bf16 v[20:23], v[28:31], v[32:35], v[20:23]
	ds_read_b128 v[28:31], v14 offset:43520
	ds_read_b128 v[44:47], v14 offset:43584
	s_waitcnt lgkmcnt(1)
	v_mfma_f32_16x16x32_bf16 v[24:27], v[28:31], v[32:35], v[24:27]
	ds_read_b128 v[28:31], v14 offset:34944
	v_mfma_f32_16x16x32_bf16 v[20:23], v[40:43], v[36:39], v[20:23]
	s_waitcnt lgkmcnt(1)
	v_mfma_f32_16x16x32_bf16 v[24:27], v[44:47], v[36:39], v[24:27]
	ds_read_b128 v[32:35], v10 offset:128
	ds_read_b128 v[36:39], v10 offset:192
	ds_read_b128 v[40:43], v14 offset:35008
	s_waitcnt lgkmcnt(2)
	v_mfma_f32_16x16x32_bf16 v[20:23], v[28:31], v[32:35], v[20:23]
	ds_read_b128 v[28:31], v14 offset:43648
	ds_read_b128 v[44:47], v14 offset:43712
	s_waitcnt vmcnt(3)
	ds_write_b128 v8, v[56:59] offset:17408
	s_waitcnt vmcnt(2)
	ds_write_b128 v8, v[60:63] offset:17536
	s_waitcnt vmcnt(1)
	ds_write_b128 v8, v[80:83] offset:52224
	s_waitcnt vmcnt(0)
	ds_write_b128 v8, v[96:99] offset:52352
	s_waitcnt lgkmcnt(0)
	v_mfma_f32_16x16x32_bf16 v[24:27], v[28:31], v[32:35], v[24:27]
	s_barrier
	ds_read_b128 v[28:31], v12 offset:52224
	v_mfma_f32_16x16x32_bf16 v[20:23], v[40:43], v[36:39], v[20:23]
	v_mfma_f32_16x16x32_bf16 v[24:27], v[44:47], v[36:39], v[24:27]
	ds_read_b128 v[32:35], v11
	ds_read_b128 v[36:39], v11 offset:64
	ds_read_b128 v[40:43], v12 offset:52288
	s_waitcnt lgkmcnt(2)
	v_mfma_f32_16x16x32_bf16 v[20:23], v[28:31], v[32:35], v[20:23]
	ds_read_b128 v[28:31], v12 offset:60928
	ds_read_b128 v[44:47], v12 offset:60992
	s_waitcnt lgkmcnt(1)
	v_mfma_f32_16x16x32_bf16 v[24:27], v[28:31], v[32:35], v[24:27]
	ds_read_b128 v[28:31], v12 offset:52352
	v_mfma_f32_16x16x32_bf16 v[20:23], v[40:43], v[36:39], v[20:23]
	s_waitcnt lgkmcnt(1)
	v_mfma_f32_16x16x32_bf16 v[24:27], v[44:47], v[36:39], v[24:27]
	ds_read_b128 v[32:35], v11 offset:128
	ds_read_b128 v[36:39], v11 offset:192
	ds_read_b128 v[40:43], v12 offset:52416
	s_waitcnt lgkmcnt(2)
	v_mfma_f32_16x16x32_bf16 v[20:23], v[28:31], v[32:35], v[20:23]
	ds_read_b128 v[28:31], v12 offset:61056
	ds_read_b128 v[44:47], v12 offset:61120
	s_waitcnt lgkmcnt(0)
	s_barrier
	v_mfma_f32_16x16x32_bf16 v[24:27], v[28:31], v[32:35], v[24:27]
	v_or_b32_e32 v28, s1, v13
	v_mov_b32_e32 v29, v3
	v_lshl_add_u64 v[30:31], s[58:59], 0, v[2:3]
	v_lshlrev_b64 v[28:29], 1, v[28:29]
	v_lshl_add_u64 v[30:31], v[30:31], 0, v[28:29]
	global_load_dwordx2 v[32:33], v[30:31], off
	v_mfma_f32_16x16x32_bf16 v[20:23], v[40:43], v[36:39], v[20:23]
	global_load_dwordx2 v[30:31], v[30:31], off offset:64
	v_cmp_lt_i32_e64 s[0:1], v16, v17
	s_waitcnt vmcnt(1)
	v_lshlrev_b32_e32 v34, 16, v32
	v_and_b32_e32 v35, 0xffff0000, v32
	v_lshlrev_b32_e32 v32, 16, v33
	v_and_b32_e32 v33, 0xffff0000, v33
	s_nop 0
	v_pk_fma_f32 v[20:21], v[34:35], s[4:5], v[20:21] op_sel_hi:[1,0,1]
	v_mfma_f32_16x16x32_bf16 v[24:27], v[44:47], v[36:39], v[24:27]
	v_fma_f32 v22, v32, s4, v22
	v_fma_f32 v23, v33, s4, v23
	v_cvt_pk_bf16_f32 v32, v20, v21
	v_lshl_add_u64 v[34:35], s[94:95], 0, v[2:3]
	v_add_f32_e32 v2, v20, v21
	v_mul_f32_e32 v21, v21, v21
	v_fmac_f32_e32 v21, v20, v20
	v_mul_f32_e32 v20, v23, v23
	v_lshl_add_u64 v[28:29], v[34:35], 0, v[28:29]
	v_add_f32_e32 v34, v22, v23
	v_fmac_f32_e32 v20, v22, v22
	v_cvt_pk_bf16_f32 v33, v22, v23
	v_add_f32_e32 v2, v2, v34
	v_add_f32_e32 v34, v21, v20
	s_waitcnt vmcnt(0)
	v_lshlrev_b32_e32 v20, 16, v30
	v_and_b32_e32 v21, 0xffff0000, v30
	v_lshlrev_b32_e32 v22, 16, v31
	v_and_b32_e32 v23, 0xffff0000, v31
	v_pk_fma_f32 v[26:27], v[22:23], s[4:5], v[26:27] op_sel_hi:[1,0,1]
	v_pk_fma_f32 v[24:25], v[20:21], s[4:5], v[24:25] op_sel_hi:[1,0,1]
	v_add_f32_e32 v21, v26, v27
	v_add_f32_e32 v20, v24, v25
	v_add_f32_e32 v2, 0, v2
	v_add_f32_e32 v20, v20, v21
	v_add_f32_e32 v2, v2, v20
	v_mul_f32_e32 v20, v25, v25
	v_mul_f32_e32 v23, v27, v27
	v_fmac_f32_e32 v20, v24, v24
	v_fmac_f32_e32 v23, v26, v26
	v_cndmask_b32_e64 v21, v15, v16, s[0:1]
	v_add_f32_e32 v20, v20, v23
	v_lshlrev_b32_e32 v21, 2, v21
	v_add_f32_e32 v23, v34, v20
	ds_bpermute_b32 v22, v21, v2
	ds_bpermute_b32 v21, v21, v23
	v_cmp_lt_i32_e64 s[0:1], v18, v17
	global_store_dwordx2 v[28:29], v[32:33], off sc1
	v_cvt_pk_bf16_f32 v24, v24, v25
	s_waitcnt lgkmcnt(1)
	v_add_f32_e32 v2, v2, v22
	v_cndmask_b32_e64 v20, v15, v18, s[0:1]
	v_lshlrev_b32_e32 v22, 2, v20
	s_waitcnt lgkmcnt(0)
	v_add_f32_e32 v21, v23, v21
	ds_bpermute_b32 v20, v22, v2
	ds_bpermute_b32 v22, v22, v21
	v_cvt_pk_bf16_f32 v25, v26, v27
	global_store_dwordx2 v[28:29], v[24:25], off offset:64 sc1
	s_and_saveexec_b64 s[0:1], vcc
	s_cbranch_execz .LBB0_1019
	s_waitcnt lgkmcnt(1)
	v_add_f32_e32 v2, v2, v20
	v_lshlrev_b32_e32 v19, 3, v19
	s_waitcnt lgkmcnt(0)
	v_add_f32_e32 v21, v21, v22
	global_atomic_add_f32 v19, v2, s[82:83]
	global_atomic_add_f32 v19, v21, s[82:83] offset:4
	s_branch .LBB0_1019

.LBB0_1057:
	s_andn2_saveexec_b64 s[4:5], s[4:5]
	s_cbranch_execz .LBB0_1077
	s_mov_b64 s[4:5], exec
	s_waitcnt lgkmcnt(0)
	s_waitcnt vmcnt(0)
	v_mbcnt_lo_u32_b32 v2, s4, 0
	v_mbcnt_hi_u32_b32 v2, s5, v2
	v_cmp_eq_u32_e32 vcc, 0, v2
	s_and_saveexec_b64 s[6:7], vcc
	s_cbranch_execz .LBB0_1060
	s_bcnt1_i32_b64 s4, s[4:5]
	v_mov_b32_e32 v3, 0x16ef000
	v_mov_b32_e32 v4, s4
	global_atomic_add v3, v3, v4, s[86:87] offset:1024 sc0

.LBB0_1110:
	s_ashr_i32 s7, s2, 2
	s_and_b32 s6, s2, 4
	s_and_b32 s7, s7, -8
	s_or_b32 s6, s7, s6
	s_ashr_i32 s6, s6, 2
	s_lshl_b32 s8, s2, 5
	s_lshl_b32 s7, s6, 8
	s_and_b32 s8, s8, 0x60
	v_add_u32_e32 v10, s7, v60
	s_and_b32 s9, s3, 0xc0
	v_or_b32_e32 v10, s8, v10
	s_bitset1_b32 s9, 14
	v_ashrrev_i32_e32 v11, 31, v10
	v_add_lshl_u32 v50, s9, v1, 11
	v_lshlrev_b64 v[10:11], 11, v[10:11]
	v_lshl_add_u64 v[56:57], v[52:53], 0, v[50:51]
	v_lshl_add_u64 v[58:59], v[54:55], 0, v[10:11]
	global_load_dwordx4 v[2:5], v[56:57], off
	global_load_dwordx4 v[6:9], v[56:57], off offset:128
	global_load_dwordx4 v[18:21], v[56:57], off offset:256
	global_load_dwordx4 v[22:25], v[56:57], off offset:384
	global_load_dwordx4 v[34:37], v[56:57], off offset:512
	global_load_dwordx4 v[38:41], v[56:57], off offset:640
	global_load_dwordx4 v[68:71], v[56:57], off offset:768
	global_load_dwordx4 v[72:75], v[56:57], off offset:896
	global_load_dwordx4 v[10:13], v[58:59], off
	global_load_dwordx4 v[14:17], v[58:59], off offset:128
	global_load_dwordx4 v[26:29], v[58:59], off offset:256
	global_load_dwordx4 v[30:33], v[58:59], off offset:384
	global_load_dwordx4 v[42:45], v[58:59], off offset:512
	global_load_dwordx4 v[46:49], v[58:59], off offset:640
	global_load_dwordx4 v[76:79], v[58:59], off offset:768
	global_load_dwordx4 v[80:83], v[58:59], off offset:896
	v_add_u32_e32 v50, s9, v62
	s_add_i32 s2, s2, s1
	s_add_i32 s3, s3, s4
	s_cmpk_lt_i32 s2, 0x160
	s_waitcnt vmcnt(0)
	ds_write_b128 v61, v[2:5]
	ds_write_b128 v61, v[6:9] offset:128
	ds_write_b128 v61, v[10:13] offset:34816
	ds_write_b128 v61, v[14:17] offset:34944
	s_waitcnt lgkmcnt(0)
	s_barrier
	ds_read_b128 v[2:5], v67 offset:34816
	ds_read_b128 v[10:13], v67 offset:43520
	ds_read_b128 v[14:17], v63
	ds_read_b128 v[84:87], v63 offset:64
	ds_read_b128 v[88:91], v67 offset:34880
	s_waitcnt lgkmcnt(2)
	v_mfma_f32_16x16x32_bf16 v[92:95], v[2:5], v[14:17], 0
	global_load_dwordx4 v[2:5], v[56:57], off offset:1024
	global_load_dwordx4 v[6:9], v[56:57], off offset:1152
	ds_read_b128 v[96:99], v67 offset:43584
	v_mfma_f32_16x16x32_bf16 v[100:103], v[10:13], v[14:17], 0
	global_load_dwordx4 v[10:13], v[58:59], off offset:1024
	global_load_dwordx4 v[14:17], v[58:59], off offset:1152
	ds_read_b128 v[104:107], v67 offset:34944
	s_waitcnt lgkmcnt(2)
	v_mfma_f32_16x16x32_bf16 v[88:91], v[88:91], v[84:87], v[92:95]
	s_nop 2
	ds_read_b128 v[92:95], v67 offset:43648
	ds_read_b128 v[108:111], v63 offset:128
	ds_read_b128 v[112:115], v63 offset:192
	s_waitcnt lgkmcnt(4)
	v_mfma_f32_16x16x32_bf16 v[84:87], v[96:99], v[84:87], v[100:103]
	ds_read_b128 v[96:99], v67 offset:35008
	s_nop 1
	ds_read_b128 v[100:103], v67 offset:43712
	ds_write_b128 v61, v[18:21] offset:17408
	ds_write_b128 v61, v[22:25] offset:17536
	ds_write_b128 v61, v[26:29] offset:52224
	ds_write_b128 v61, v[30:33] offset:52352
	s_waitcnt lgkmcnt(7)
	v_mfma_f32_16x16x32_bf16 v[18:21], v[104:107], v[108:111], v[88:91]
	s_waitcnt lgkmcnt(0)
	s_barrier
	v_mfma_f32_16x16x32_bf16 v[22:25], v[92:95], v[108:111], v[84:87]
	ds_read_b128 v[26:29], v65 offset:52224
	ds_read_b128 v[30:33], v65 offset:60928
	v_mfma_f32_16x16x32_bf16 v[18:21], v[96:99], v[112:115], v[18:21]
	ds_read_b128 v[88:91], v64
	ds_read_b128 v[92:95], v64 offset:64
	ds_read_b128 v[96:99], v65 offset:52288
	v_mfma_f32_16x16x32_bf16 v[84:87], v[100:103], v[112:115], v[22:25]
	s_waitcnt lgkmcnt(2)
	v_mfma_f32_16x16x32_bf16 v[100:103], v[26:29], v[88:91], v[18:21]
	s_nop 0
	global_load_dwordx4 v[22:25], v[56:57], off offset:1280
	s_nop 0
	global_load_dwordx4 v[18:21], v[56:57], off offset:1408
	ds_read_b128 v[104:107], v65 offset:60992
	v_mfma_f32_16x16x32_bf16 v[84:87], v[30:33], v[88:91], v[84:87]
	global_load_dwordx4 v[26:29], v[58:59], off offset:1280
	global_load_dwordx4 v[30:33], v[58:59], off offset:1408
	ds_read_b128 v[88:91], v65 offset:52352
	s_waitcnt lgkmcnt(2)
	v_mfma_f32_16x16x32_bf16 v[96:99], v[96:99], v[92:95], v[100:103]
	s_nop 2
	ds_read_b128 v[100:103], v65 offset:61056
	ds_read_b128 v[108:111], v64 offset:128
	ds_read_b128 v[112:115], v64 offset:192
	s_waitcnt lgkmcnt(4)
	v_mfma_f32_16x16x32_bf16 v[84:87], v[104:107], v[92:95], v[84:87]
	ds_read_b128 v[92:95], v65 offset:52416
	ds_read_b128 v[104:107], v65 offset:61120
	ds_write_b128 v61, v[34:37]
	ds_write_b128 v61, v[38:41] offset:128
	ds_write_b128 v61, v[42:45] offset:34816
	ds_write_b128 v61, v[46:49] offset:34944
	s_waitcnt lgkmcnt(7)
	v_mfma_f32_16x16x32_bf16 v[34:37], v[88:91], v[108:111], v[96:99]
	s_waitcnt lgkmcnt(0)
	s_barrier
	v_mfma_f32_16x16x32_bf16 v[38:41], v[100:103], v[108:111], v[84:87]
	ds_read_b128 v[42:45], v67 offset:34816
	ds_read_b128 v[46:49], v67 offset:43520
	v_mfma_f32_16x16x32_bf16 v[34:37], v[92:95], v[112:115], v[34:37]
	ds_read_b128 v[88:91], v63
	ds_read_b128 v[92:95], v63 offset:64
	ds_read_b128 v[96:99], v67 offset:34880
	v_mfma_f32_16x16x32_bf16 v[84:87], v[104:107], v[112:115], v[38:41]
	s_waitcnt lgkmcnt(2)
	v_mfma_f32_16x16x32_bf16 v[100:103], v[42:45], v[88:91], v[34:37]
	s_nop 0
	global_load_dwordx4 v[38:41], v[56:57], off offset:1536
	s_nop 0
	global_load_dwordx4 v[34:37], v[56:57], off offset:1664
	ds_read_b128 v[104:107], v67 offset:43584
	v_mfma_f32_16x16x32_bf16 v[84:87], v[46:49], v[88:91], v[84:87]
	global_load_dwordx4 v[42:45], v[58:59], off offset:1536
	global_load_dwordx4 v[46:49], v[58:59], off offset:1664
	ds_read_b128 v[88:91], v67 offset:34944
	s_waitcnt lgkmcnt(2)
	v_mfma_f32_16x16x32_bf16 v[96:99], v[96:99], v[92:95], v[100:103]
	s_nop 2
	ds_read_b128 v[100:103], v67 offset:43648
	ds_read_b128 v[108:111], v63 offset:128
	ds_read_b128 v[112:115], v63 offset:192
	s_waitcnt lgkmcnt(4)
	v_mfma_f32_16x16x32_bf16 v[84:87], v[104:107], v[92:95], v[84:87]
	ds_read_b128 v[92:95], v67 offset:35008
	ds_read_b128 v[104:107], v67 offset:43712
	ds_write_b128 v61, v[68:71] offset:17408
	ds_write_b128 v61, v[72:75] offset:17536
	ds_write_b128 v61, v[76:79] offset:52224
	ds_write_b128 v61, v[80:83] offset:52352
	s_waitcnt lgkmcnt(0)
	s_barrier
	ds_read_b128 v[76:79], v65 offset:52224
	v_mfma_f32_16x16x32_bf16 v[68:71], v[88:91], v[108:111], v[96:99]
	v_mfma_f32_16x16x32_bf16 v[72:75], v[100:103], v[108:111], v[84:87]
	ds_read_b128 v[80:83], v64
	s_nop 1
	ds_read_b128 v[84:87], v64 offset:64
	ds_read_b128 v[88:91], v65 offset:52288
	v_or_b32_e32 v102, s8, v66
	v_or_b32_e32 v100, s7, v102
	v_mfma_f32_16x16x32_bf16 v[68:71], v[92:95], v[112:115], v[68:71]
	v_lshlrev_b32_e32 v103, 3, v50
	v_ashrrev_i32_e32 v101, 31, v100
	v_mul_u32_u24_e32 v50, 0x1600, v50
	v_mfma_f32_16x16x32_bf16 v[72:75], v[104:107], v[112:115], v[72:75]
	s_waitcnt lgkmcnt(2)
	v_mfma_f32_16x16x32_bf16 v[68:71], v[76:79], v[80:83], v[68:71]
	ds_read_b128 v[76:79], v65 offset:60928
	ds_read_b128 v[92:95], v65 offset:60992
	s_waitcnt lgkmcnt(1)
	v_mfma_f32_16x16x32_bf16 v[72:75], v[76:79], v[80:83], v[72:75]
	ds_read_b128 v[76:79], v65 offset:52352
	v_mfma_f32_16x16x32_bf16 v[68:71], v[88:91], v[84:87], v[68:71]
	s_waitcnt lgkmcnt(1)
	v_mfma_f32_16x16x32_bf16 v[72:75], v[92:95], v[84:87], v[72:75]
	ds_read_b128 v[80:83], v64 offset:128
	ds_read_b128 v[84:87], v64 offset:192
	ds_read_b128 v[88:91], v65 offset:52416
	s_waitcnt lgkmcnt(2)
	v_mfma_f32_16x16x32_bf16 v[68:71], v[76:79], v[80:83], v[68:71]
	ds_read_b128 v[76:79], v65 offset:61056
	ds_read_b128 v[92:95], v65 offset:61120
	s_waitcnt lgkmcnt(1)
	v_mfma_f32_16x16x32_bf16 v[72:75], v[76:79], v[80:83], v[72:75]
	global_load_dwordx4 v[76:79], v[56:57], off offset:1792
	v_mfma_f32_16x16x32_bf16 v[68:71], v[88:91], v[84:87], v[68:71]
	global_load_dwordx4 v[80:83], v[56:57], off offset:1920
	global_load_dwordx4 v[88:91], v[58:59], off offset:1792
	global_load_dwordx4 v[96:99], v[58:59], off offset:1920
	s_waitcnt vmcnt(15)
	ds_write_b128 v61, v[2:5]
	s_waitcnt vmcnt(14)
	ds_write_b128 v61, v[6:9] offset:128
	s_waitcnt vmcnt(13)
	ds_write_b128 v61, v[10:13] offset:34816
	s_waitcnt vmcnt(12)
	ds_write_b128 v61, v[14:17] offset:34944
	s_waitcnt lgkmcnt(0)
	s_barrier
	ds_read_b128 v[2:5], v67 offset:34816
	ds_read_b128 v[6:9], v63
	ds_read_b128 v[10:13], v63 offset:64
	ds_read_b128 v[14:17], v67 offset:34880
	v_mfma_f32_16x16x32_bf16 v[56:59], v[92:95], v[84:87], v[72:75]
	v_lshlrev_b64 v[92:93], 2, v[100:101]
	s_waitcnt lgkmcnt(2)
	v_mfma_f32_16x16x32_bf16 v[2:5], v[2:5], v[6:9], v[68:71]
	s_nop 2
	ds_read_b128 v[68:71], v67 offset:43520
	ds_read_b128 v[72:75], v67 offset:43584
	s_waitcnt lgkmcnt(1)
	v_mfma_f32_16x16x32_bf16 v[6:9], v[68:71], v[6:9], v[56:59]
	s_nop 2
	ds_read_b128 v[56:59], v67 offset:34944
	v_mfma_f32_16x16x32_bf16 v[2:5], v[14:17], v[10:13], v[2:5]
	ds_read_b128 v[14:17], v67 offset:43648
	ds_read_b128 v[68:71], v63 offset:128
	ds_read_b128 v[84:87], v63 offset:192
	s_waitcnt lgkmcnt(4)
	v_mfma_f32_16x16x32_bf16 v[6:9], v[72:75], v[10:13], v[6:9]
	ds_read_b128 v[10:13], v67 offset:35008
	ds_read_b128 v[72:75], v67 offset:43712
	s_waitcnt vmcnt(11)
	ds_write_b128 v61, v[22:25] offset:17408
	s_waitcnt vmcnt(10)
	ds_write_b128 v61, v[18:21] offset:17536
	s_waitcnt vmcnt(9)
	ds_write_b128 v61, v[26:29] offset:52224
	s_waitcnt vmcnt(8)
	ds_write_b128 v61, v[30:33] offset:52352
	s_waitcnt lgkmcnt(7)
	v_mfma_f32_16x16x32_bf16 v[2:5], v[56:59], v[68:71], v[2:5]
	s_waitcnt lgkmcnt(0)
	s_barrier
	v_mfma_f32_16x16x32_bf16 v[2:5], v[10:13], v[84:87], v[2:5]
	ds_read_b128 v[10:13], v65 offset:52224
	v_mfma_f32_16x16x32_bf16 v[6:9], v[14:17], v[68:71], v[6:9]
	ds_read_b128 v[14:17], v64
	ds_read_b128 v[18:21], v64 offset:64
	ds_read_b128 v[22:25], v65 offset:52288
	v_lshl_add_u64 v[68:69], s[14:15], 0, v[92:93]
	v_lshl_add_u64 v[70:71], s[18:19], 0, v[92:93]
	v_mfma_f32_16x16x32_bf16 v[6:9], v[72:75], v[84:87], v[6:9]
	s_waitcnt lgkmcnt(2)
	v_mfma_f32_16x16x32_bf16 v[2:5], v[10:13], v[14:17], v[2:5]
	ds_read_b128 v[10:13], v65 offset:60928
	ds_read_b128 v[26:29], v65 offset:60992
	s_waitcnt lgkmcnt(1)
	v_mfma_f32_16x16x32_bf16 v[6:9], v[10:13], v[14:17], v[6:9]
	ds_read_b128 v[10:13], v65 offset:52352
	v_mfma_f32_16x16x32_bf16 v[2:5], v[22:25], v[18:21], v[2:5]
	ds_read_b128 v[14:17], v65 offset:61056
	ds_read_b128 v[22:25], v64 offset:128
	ds_read_b128 v[30:33], v64 offset:192
	s_waitcnt lgkmcnt(4)
	v_mfma_f32_16x16x32_bf16 v[6:9], v[26:29], v[18:21], v[6:9]
	ds_read_b128 v[18:21], v65 offset:52416
	ds_read_b128 v[26:29], v65 offset:61120
	s_waitcnt vmcnt(7)
	ds_write_b128 v61, v[38:41]
	s_waitcnt vmcnt(6)
	ds_write_b128 v61, v[34:37] offset:128
	s_waitcnt vmcnt(5)
	ds_write_b128 v61, v[42:45] offset:34816
	s_waitcnt vmcnt(4)
	ds_write_b128 v61, v[46:49] offset:34944
	s_waitcnt lgkmcnt(7)
	v_mfma_f32_16x16x32_bf16 v[2:5], v[10:13], v[22:25], v[2:5]
	s_waitcnt lgkmcnt(0)
	s_barrier
	v_mfma_f32_16x16x32_bf16 v[6:9], v[14:17], v[22:25], v[6:9]
	ds_read_b128 v[10:13], v67 offset:34816
	ds_read_b128 v[14:17], v67 offset:43520
	v_mfma_f32_16x16x32_bf16 v[2:5], v[18:21], v[30:33], v[2:5]
	v_mfma_f32_16x16x32_bf16 v[6:9], v[26:29], v[30:33], v[6:9]
	ds_read_b128 v[18:21], v63
	ds_read_b128 v[22:25], v63 offset:64
	ds_read_b128 v[26:29], v67 offset:34880
	s_waitcnt lgkmcnt(2)
	v_mfma_f32_16x16x32_bf16 v[2:5], v[10:13], v[18:21], v[2:5]
	ds_read_b128 v[10:13], v67 offset:43584
	ds_read_b128 v[30:33], v63 offset:128
	ds_read_b128 v[34:37], v67 offset:43648
	v_mfma_f32_16x16x32_bf16 v[6:9], v[14:17], v[18:21], v[6:9]
	ds_read_b128 v[14:17], v63 offset:192
	ds_read_b128 v[18:21], v67 offset:34944
	ds_read_b128 v[38:41], v67 offset:35008
	s_waitcnt lgkmcnt(6)
	v_mfma_f32_16x16x32_bf16 v[2:5], v[26:29], v[22:25], v[2:5]
	ds_read_b128 v[26:29], v67 offset:43712
	s_waitcnt vmcnt(3)
	ds_write_b128 v61, v[76:79] offset:17408
	s_waitcnt vmcnt(2)
	ds_write_b128 v61, v[80:83] offset:17536
	s_waitcnt vmcnt(1)
	ds_write_b128 v61, v[88:91] offset:52224
	s_waitcnt vmcnt(0)
	ds_write_b128 v61, v[96:99] offset:52352
	s_waitcnt lgkmcnt(10)
	v_mfma_f32_16x16x32_bf16 v[6:9], v[10:13], v[22:25], v[6:9]
	s_waitcnt lgkmcnt(0)
	s_barrier
	v_mfma_f32_16x16x32_bf16 v[2:5], v[18:21], v[30:33], v[2:5]
	ds_read_b128 v[10:13], v64
	v_mfma_f32_16x16x32_bf16 v[6:9], v[34:37], v[30:33], v[6:9]
	ds_read_b128 v[18:21], v64 offset:64
	ds_read_b128 v[22:25], v65 offset:52224
	ds_read_b128 v[30:33], v65 offset:52288
	v_mfma_f32_16x16x32_bf16 v[2:5], v[38:41], v[14:17], v[2:5]
	ds_read_b128 v[34:37], v65 offset:60928
	ds_read_b128 v[38:41], v65 offset:60992
	ds_read_b128 v[42:45], v64 offset:128
	v_mfma_f32_16x16x32_bf16 v[6:9], v[26:29], v[14:17], v[6:9]
	ds_read_b128 v[14:17], v64 offset:192
	ds_read_b128 v[26:29], v65 offset:52352
	ds_read_b128 v[46:49], v65 offset:52416
	s_waitcnt lgkmcnt(7)
	v_mfma_f32_16x16x32_bf16 v[2:5], v[22:25], v[10:13], v[2:5]
	ds_read_b128 v[22:25], v65 offset:61056
	ds_read_b128 v[56:59], v65 offset:61120
	s_waitcnt lgkmcnt(0)
	s_barrier
	v_mfma_f32_16x16x32_bf16 v[6:9], v[34:37], v[10:13], v[6:9]
	global_load_dwordx2 v[34:35], v103, s[82:83]
	global_load_dwordx4 v[10:13], v[68:69], off
	v_mfma_f32_16x16x32_bf16 v[2:5], v[30:33], v[18:21], v[2:5]
	s_waitcnt vmcnt(0)
	v_xor_b32_e32 v13, 0x80000000, v13
	v_mfma_f32_16x16x32_bf16 v[6:9], v[38:41], v[18:21], v[6:9]
	global_load_dwordx4 v[18:21], v[68:69], off offset:512
	global_load_dwordx4 v[30:33], v[70:71], off
	v_xor_b32_e32 v12, 0x80000000, v12
	v_mfma_f32_16x16x32_bf16 v[2:5], v[26:29], v[42:45], v[2:5]
	global_load_dwordx4 v[26:29], v[70:71], off offset:512
	v_mfma_f32_16x16x32_bf16 v[6:9], v[22:25], v[42:45], v[6:9]
	v_lshl_or_b32 v22, s6, 7, v102
	v_lshl_add_u64 v[24:25], s[58:59], 0, v[50:51]
	v_ashrrev_i32_e32 v23, 31, v22
	v_mfma_f32_16x16x32_bf16 v[2:5], v[46:49], v[14:17], v[2:5]
	v_lshl_add_u64 v[22:23], v[22:23], 1, v[24:25]
	v_mfma_f32_16x16x32_bf16 v[6:9], v[56:59], v[14:17], v[6:9]
	v_mul_f32_e64 v14, v34, s0
	v_mul_f32_e64 v15, v35, s0
	v_fma_f32 v16, -v14, v14, v15
	s_nop 2
	v_pk_fma_f32 v[2:3], v[10:11], v[14:15], v[2:3] op_sel_hi:[1,0,1] neg_lo:[1,0,0] neg_hi:[1,0,0]
	v_add_f32_e32 v10, 0x3727c5ac, v16
	v_mul_f32_e32 v11, 0x4b800000, v10
	v_cmp_gt_f32_e32 vcc, s5, v10
	v_pk_fma_f32 v[4:5], v[12:13], v[14:15], v[4:5] op_sel_hi:[1,0,1]
	s_waitcnt vmcnt(2)
	v_pk_fma_f32 v[8:9], v[14:15], v[20:21], v[8:9] op_sel_hi:[0,1,1] neg_lo:[1,0,0] neg_hi:[1,0,0]
	v_cndmask_b32_e32 v10, v10, v11, vcc
	v_rsq_f32_e32 v10, v10
	v_pk_fma_f32 v[6:7], v[14:15], v[18:19], v[6:7] op_sel_hi:[0,1,1] neg_lo:[1,0,0] neg_hi:[1,0,0]
	v_mul_f32_e32 v11, 0x45800000, v10
	v_cndmask_b32_e32 v10, v10, v11, vcc
	s_waitcnt vmcnt(1)
	v_pk_fma_f32 v[2:3], v[2:3], v[10:11], v[30:31] op_sel_hi:[1,0,1]
	v_pk_fma_f32 v[4:5], v[4:5], v[10:11], v[32:33] op_sel_hi:[1,0,1]
	s_waitcnt vmcnt(0)
	v_pk_fma_f32 v[8:9], v[8:9], v[10:11], v[28:29] op_sel_hi:[1,0,1]
	v_pk_fma_f32 v[6:7], v[6:7], v[10:11], v[26:27] op_sel_hi:[1,0,1]
	v_mul_f32_e32 v10, 0xbfb8aa3b, v2
	v_mul_f32_e32 v11, 0xbfb8aa3b, v3
	v_mul_f32_e32 v12, 0xbfb8aa3b, v4
	v_mul_f32_e32 v13, 0xbfb8aa3b, v5
	v_exp_f32_e32 v10, v10
	v_exp_f32_e32 v11, v11
	v_exp_f32_e32 v12, v12
	v_exp_f32_e32 v13, v13
	v_add_f32_e32 v10, 1.0, v10
	v_add_f32_e32 v11, 1.0, v11
	v_add_f32_e32 v12, 1.0, v12
	v_add_f32_e32 v13, 1.0, v13
	v_rcp_f32_e32 v10, v10
	v_rcp_f32_e32 v11, v11
	v_rcp_f32_e32 v12, v12
	v_rcp_f32_e32 v13, v13
	v_mul_f32_e32 v2, v2, v10
	v_mul_f32_e32 v3, v3, v11
	v_mul_f32_e32 v4, v4, v12
	v_mul_f32_e32 v5, v5, v13
	v_mul_f32_e32 v2, v6, v2
	v_mul_f32_e32 v3, v7, v3
	v_mul_f32_e32 v4, v8, v4
	v_mul_f32_e32 v5, v9, v5
	v_cvt_pk_bf16_f32 v2, v2, v3
	v_cvt_pk_bf16_f32 v3, v4, v5
	global_store_dwordx2 v[22:23], v[2:3], off sc1
	s_cbranch_scc1 .LBB0_1110
